# seam2 counter + hgrn state update software-pipelined over v-tile pairs (LDS reads under MFMAs, extra operand/accumulator regs)
# speedup vs baseline: 1.0168x; 1.0168x over previous
.LBB0_525:
	s_min_u32 s54, s91, 28
	s_lshl_b32 s92, s91, 6
	s_lshl_b32 s54, s54, 6
	s_or_b32 s66, s92, 64
	s_add_i32 s58, s54, 0xc0
	s_add_u32 s54, s62, s58
	s_addc_u32 s55, s63, 0
	v_add_u32_e32 v32, v175, v162
	s_add_u32 s58, s60, s58
	ds_write_b128 v32, v[16:19]
	v_add_u32_e32 v16, v175, v163
	s_addc_u32 s59, 0, 0
	ds_write_b128 v16, v[20:23]
	v_lshl_add_u64 v[16:17], v[88:89], 0, s[66:67]
	s_add_u32 s72, s54, s86
	v_lshlrev_b64 v[16:17], 8, v[16:17]
	s_addc_u32 s73, s55, 0
	v_lshl_add_u64 v[16:17], v[90:91], 0, v[16:17]
	s_lshl_b64 s[72:73], s[72:73], 8
	global_load_dwordx2 v[100:101], v[16:17], off
	global_load_dwordx2 v[98:99], v[16:17], off offset:32
	global_load_dwordx2 v[96:97], v[16:17], off offset:64
	global_load_dwordx2 v[94:95], v[16:17], off offset:96
	v_lshl_add_u64 v[16:17], v[70:71], 0, s[72:73]
	s_lshl_b64 s[58:59], s[58:59], 11
	global_load_dword v194, v[16:17], off
	v_lshl_add_u64 v[16:17], v[72:73], 0, s[58:59]
	s_or_b32 s58, s72, 0x100
	s_mov_b32 s59, s73
	v_lshl_add_u64 v[18:19], v[70:71], 0, s[58:59]
	s_or_b32 s58, s72, 0x200
	global_load_dword v200, v[16:17], off
	global_load_dword v186, v[18:19], off
	global_load_dword v198, v[16:17], off offset:2048
	v_lshl_add_u64 v[18:19], v[70:71], 0, s[58:59]
	global_load_dword v181, v[18:19], off
	v_add_co_u32_e32 v18, vcc, s61, v16
	s_or_b32 s58, s72, 0x300
	s_nop 0
	v_addc_co_u32_e32 v19, vcc, 0, v17, vcc
	v_add_co_u32_e32 v20, vcc, s87, v16
	v_lshl_add_u64 v[22:23], v[70:71], 0, s[58:59]
	s_nop 0
	v_addc_co_u32_e32 v21, vcc, 0, v17, vcc
	s_or_b32 s58, s72, 0x400
	global_load_dword v201, v[20:21], off offset:-4096
	global_load_dword v179, v[22:23], off
	global_load_dword v185, v[18:19], off offset:2048
	v_lshl_add_u64 v[18:19], v[70:71], 0, s[58:59]
	s_or_b32 s58, s72, 0x500
	global_load_dword v177, v[18:19], off
	global_load_dword v196, v[20:21], off
	v_lshl_add_u64 v[18:19], v[70:71], 0, s[58:59]
	s_or_b32 s58, s72, 0x600
	v_add_co_u32_e32 v16, vcc, s88, v16
	global_load_dword v173, v[18:19], off
	global_load_dword v187, v[20:21], off offset:2048
	v_lshl_add_u64 v[18:19], v[70:71], 0, s[58:59]
	v_addc_co_u32_e32 v17, vcc, 0, v17, vcc
	s_or_b32 s72, s72, 0x700
	global_load_dword v166, v[18:19], off
	global_load_dword v167, v[16:17], off
	v_lshl_add_u64 v[18:19], v[70:71], 0, s[72:73]
	global_load_dword v164, v[18:19], off
	global_load_dword v165, v[16:17], off offset:2048
	v_mov_b32_e32 v17, s55
	v_or_b32_e32 v16, s54, v93
	v_lshl_add_u64 v[20:21], s[54:55], 0, v[68:69]
	v_lshlrev_b64 v[16:17], 8, v[16:17]
	v_lshlrev_b64 v[20:21], 8, v[20:21]
	v_lshl_add_u64 v[16:17], v[74:75], 0, v[16:17]
	v_lshl_add_u64 v[20:21], v[74:75], 0, v[20:21]
	global_load_dwordx4 v[16:19], v[16:17], off
	s_nop 0
	global_load_dwordx4 v[20:23], v[20:21], off
	ds_read_b128 v[56:59], v218
	ds_read_b128 v[48:51], v218 offset:64
	ds_read_b128 v[44:47], v218 offset:128
	ds_read_b128 v[40:43], v218 offset:192
	ds_read_b128 v[32:35], v204 offset:17408
	ds_read_b128 v[36:39], v204 offset:17472
	s_waitcnt lgkmcnt(1)
	v_mfma_f32_16x16x32_bf16 v[32:35], v[32:35], v[56:59], 0
	s_waitcnt lgkmcnt(0)
	v_mfma_f32_16x16x32_bf16 v[32:35], v[36:39], v[48:51], v[32:35]
	ds_read_b128 v[36:39], v204 offset:17536
	s_waitcnt lgkmcnt(0)
	v_mfma_f32_16x16x32_bf16 v[32:35], v[36:39], v[44:47], v[32:35]
	ds_read_b128 v[36:39], v204 offset:17600
	s_waitcnt lgkmcnt(0)
	v_mfma_f32_16x16x32_bf16 v[32:35], v[36:39], v[40:43], v[32:35]
	ds_read_b128 v[36:39], v204 offset:21824
	s_nop 6
	v_cndmask_b32_e64 v52, 0, v32, s[18:19]
	v_cndmask_b32_e64 v53, 0, v33, s[20:21]
	v_cndmask_b32_e64 v54, 0, v34, s[22:23]
	v_cndmask_b32_e64 v55, 0, v35, s[24:25]
	ds_read_b128 v[32:35], v204 offset:21760
	s_waitcnt lgkmcnt(0)
	v_mfma_f32_16x16x32_bf16 v[32:35], v[32:35], v[56:59], 0
	v_cvt_pk_bf16_f32 v64, v52, v53
	v_cvt_pk_bf16_f32 v65, v54, v55
	v_mfma_f32_16x16x32_bf16 v[32:35], v[36:39], v[48:51], v[32:35]
	ds_read_b128 v[36:39], v204 offset:21888
	s_waitcnt lgkmcnt(0)
	v_mfma_f32_16x16x32_bf16 v[32:35], v[36:39], v[44:47], v[32:35]
	ds_read_b128 v[36:39], v204 offset:21952
	s_waitcnt lgkmcnt(0)
	v_mfma_f32_16x16x32_bf16 v[32:35], v[36:39], v[40:43], v[32:35]
	ds_read_b128 v[36:39], v204 offset:26176
	s_nop 6
	v_cndmask_b32_e64 v60, 0, v32, s[26:27]
	v_cndmask_b32_e64 v61, 0, v33, s[28:29]
	v_cndmask_b32_e64 v62, 0, v34, s[30:31]
	v_cndmask_b32_e64 v63, 0, v35, s[34:35]
	ds_read_b128 v[32:35], v204 offset:26112
	s_waitcnt lgkmcnt(0)
	v_mfma_f32_16x16x32_bf16 v[32:35], v[32:35], v[56:59], 0
	v_cvt_pk_bf16_f32 v67, v62, v63
	v_cvt_pk_bf16_f32 v66, v60, v61
	v_mfma_f32_16x16x32_bf16 v[32:35], v[36:39], v[48:51], v[32:35]
	ds_read_b128 v[36:39], v204 offset:26240
	s_waitcnt lgkmcnt(0)
	v_mfma_f32_16x16x32_bf16 v[32:35], v[36:39], v[44:47], v[32:35]
	ds_read_b128 v[36:39], v204 offset:26304
	s_waitcnt lgkmcnt(0)
	v_mfma_f32_16x16x32_bf16 v[32:35], v[36:39], v[40:43], v[32:35]
	ds_read_b128 v[36:39], v204 offset:30528
	s_nop 6
	v_cndmask_b32_e64 v86, 0, v32, s[36:37]
	v_cndmask_b32_e64 v149, 0, v33, s[38:39]
	v_cndmask_b32_e64 v150, 0, v34, s[40:41]
	v_cndmask_b32_e64 v151, 0, v35, s[42:43]
	ds_read_b128 v[32:35], v204 offset:30464
	s_waitcnt lgkmcnt(0)
	v_mfma_f32_16x16x32_bf16 v[32:35], v[32:35], v[56:59], 0
	v_cvt_pk_bf16_f32 v60, v86, v149
	v_cvt_pk_bf16_f32 v61, v150, v151
	v_add_u32_e32 v86, v178, v203
	v_mfma_f32_16x16x32_bf16 v[32:35], v[36:39], v[48:51], v[32:35]
	ds_read_b128 v[36:39], v204 offset:30592
	s_waitcnt lgkmcnt(0)
	v_mfma_f32_16x16x32_bf16 v[32:35], v[36:39], v[44:47], v[32:35]
	ds_read_b128 v[36:39], v204 offset:30656
	s_waitcnt lgkmcnt(0)
	v_mfma_f32_16x16x32_bf16 v[32:35], v[36:39], v[40:43], v[32:35]
	s_nop 7
	v_cndmask_b32_e64 v32, 0, v32, s[44:45]
	v_cndmask_b32_e64 v33, 0, v33, s[46:47]
	v_cndmask_b32_e64 v34, 0, v34, s[48:49]
	v_cndmask_b32_e64 v35, 0, v35, s[50:51]
	v_cvt_pk_bf16_f32 v62, v32, v33
	v_cvt_pk_bf16_f32 v63, v34, v35
	ds_read_b64_tr_b16 v[32:33], v205 offset:34816
	ds_read_b64_tr_b16 v[34:35], v205 offset:39168
	ds_read_b64_tr_b16 v[36:37], v205 offset:43520
	ds_read_b64_tr_b16 v[38:39], v205 offset:47872
	s_waitcnt lgkmcnt(2)
	v_mfma_f32_16x16x32_bf16 v[32:35], v[32:35], v[64:67], 0
	s_waitcnt lgkmcnt(0)
	v_mfma_f32_16x16x32_bf16 v[32:35], v[36:39], v[60:63], v[32:35]
	ds_read_b128 v[36:39], v219
	s_waitcnt lgkmcnt(0)
	v_mfma_f32_16x16x32_bf16 v[32:35], v[36:39], v[56:59], v[32:35]
	ds_read_b128 v[36:39], v219 offset:64
	s_waitcnt lgkmcnt(0)
	v_mfma_f32_16x16x32_bf16 v[32:35], v[36:39], v[48:51], v[32:35]
	ds_read_b128 v[36:39], v219 offset:128
	s_waitcnt lgkmcnt(0)
	v_mfma_f32_16x16x32_bf16 v[32:35], v[36:39], v[44:47], v[32:35]
	ds_read_b128 v[36:39], v219 offset:192
	s_waitcnt lgkmcnt(0)
	v_mfma_f32_16x16x32_bf16 v[32:35], v[36:39], v[40:43], v[32:35]
	ds_read_b64_tr_b16 v[36:37], v206 offset:34816
	ds_read_b64_tr_b16 v[38:39], v206 offset:39168
	ds_read_b64_tr_b16 v[52:53], v206 offset:43520
	ds_read_b64_tr_b16 v[54:55], v206 offset:47872
	s_waitcnt lgkmcnt(2)
	v_mfma_f32_16x16x32_bf16 v[36:39], v[36:39], v[64:67], 0
	s_waitcnt lgkmcnt(0)
	v_mfma_f32_16x16x32_bf16 v[36:39], v[52:55], v[60:63], v[36:39]
	ds_read_b128 v[52:55], v220
	s_waitcnt lgkmcnt(0)
	v_mfma_f32_16x16x32_bf16 v[36:39], v[52:55], v[56:59], v[36:39]
	ds_read_b128 v[52:55], v220 offset:64
	s_waitcnt lgkmcnt(0)
	v_mfma_f32_16x16x32_bf16 v[36:39], v[52:55], v[48:51], v[36:39]
	ds_read_b128 v[52:55], v220 offset:128
	s_waitcnt lgkmcnt(0)
	v_mfma_f32_16x16x32_bf16 v[36:39], v[52:55], v[44:47], v[36:39]
	ds_read_b128 v[52:55], v220 offset:192
	s_waitcnt lgkmcnt(0)
	v_mfma_f32_16x16x32_bf16 v[36:39], v[52:55], v[40:43], v[36:39]
	ds_read_b64_tr_b16 v[52:53], v207 offset:34816
	ds_read_b64_tr_b16 v[54:55], v207 offset:39168
	ds_read_b64_tr_b16 v[150:151], v207 offset:43520
	ds_read_b64_tr_b16 v[152:153], v207 offset:47872
	s_waitcnt lgkmcnt(2)
	v_mfma_f32_16x16x32_bf16 v[52:55], v[52:55], v[64:67], 0
	s_waitcnt lgkmcnt(0)
	v_mfma_f32_16x16x32_bf16 v[52:55], v[150:153], v[60:63], v[52:55]
	ds_read_b128 v[150:153], v221
	s_waitcnt lgkmcnt(0)
	v_mfma_f32_16x16x32_bf16 v[52:55], v[150:153], v[56:59], v[52:55]
	ds_read_b128 v[150:153], v221 offset:64
	s_waitcnt lgkmcnt(0)
	v_mfma_f32_16x16x32_bf16 v[52:55], v[150:153], v[48:51], v[52:55]
	ds_read_b128 v[150:153], v221 offset:128
	s_waitcnt lgkmcnt(0)
	v_mfma_f32_16x16x32_bf16 v[52:55], v[150:153], v[44:47], v[52:55]
	ds_read_b128 v[150:153], v221 offset:192
	s_waitcnt lgkmcnt(0)
	v_mfma_f32_16x16x32_bf16 v[52:55], v[150:153], v[40:43], v[52:55]
	ds_read_b64_tr_b16 v[150:151], v208 offset:34816
	ds_read_b64_tr_b16 v[152:153], v208 offset:39168
	s_waitcnt lgkmcnt(0)
	v_mfma_f32_16x16x32_bf16 v[64:67], v[150:153], v[64:67], 0
	ds_read_b64_tr_b16 v[150:151], v208 offset:43520
	ds_read_b64_tr_b16 v[152:153], v208 offset:47872
	s_waitcnt lgkmcnt(0)
	v_mfma_f32_16x16x32_bf16 v[60:63], v[150:153], v[60:63], v[64:67]
	s_nop 3
	ds_read_b128 v[64:67], v222
	s_waitcnt lgkmcnt(0)
	v_mfma_f32_16x16x32_bf16 v[56:59], v[64:67], v[56:59], v[60:63]
	s_nop 2
	ds_read_b128 v[60:63], v222 offset:64
	s_waitcnt lgkmcnt(0)
	v_mfma_f32_16x16x32_bf16 v[48:51], v[60:63], v[48:51], v[56:59]
	s_nop 2
	ds_read_b128 v[56:59], v222 offset:128
	s_waitcnt lgkmcnt(0)
	v_mfma_f32_16x16x32_bf16 v[44:47], v[56:59], v[44:47], v[48:51]
	s_nop 2
	ds_read_b128 v[48:51], v222 offset:192
	s_waitcnt lgkmcnt(0)
	v_mfma_f32_16x16x32_bf16 v[40:43], v[48:51], v[40:43], v[44:47]
	ds_read_b64_tr_b16 v[60:61], v209 offset:17408
	ds_read_b64_tr_b16 v[62:63], v209 offset:18496
	ds_read_b64_tr_b16 v[48:49], v209 offset:26112
	ds_read_b64_tr_b16 v[50:51], v209 offset:27200
	ds_read_b128 v[44:47], v180
	ds_read_b128 v[56:59], v182
	ds_read_b64_tr_b16 v[244:245], v86 offset:34816
	ds_read_b64_tr_b16 v[246:247], v86 offset:35904
	ds_read_b64_tr_b16 v[228:229], v86 offset:34848
	ds_read_b64_tr_b16 v[230:231], v86 offset:35936
	ds_read_b64_tr_b16 v[150:151], v86 offset:43520
	ds_read_b64_tr_b16 v[152:153], v86 offset:44608
	ds_read_b64_tr_b16 v[240:241], v86 offset:43552
	ds_read_b64_tr_b16 v[242:243], v86 offset:44640
	s_waitcnt lgkmcnt(6)
	v_mfma_f32_16x16x32_bf16 v[64:67], v[60:63], v[244:247], 0
	s_waitcnt lgkmcnt(4)
	v_mfma_f32_16x16x32_bf16 v[236:239], v[60:63], v[228:231], 0
	s_waitcnt lgkmcnt(2)
	v_mfma_f32_16x16x32_bf16 v[64:67], v[48:51], v[150:153], v[64:67]
	s_waitcnt lgkmcnt(0)
	v_mfma_f32_16x16x32_bf16 v[236:239], v[48:51], v[240:243], v[236:239]
	ds_read_b64_tr_b16 v[244:245], v86 offset:34880
	ds_read_b64_tr_b16 v[246:247], v86 offset:35968
	ds_read_b64_tr_b16 v[228:229], v86 offset:34912
	ds_read_b64_tr_b16 v[230:231], v86 offset:36000
	ds_read_b64_tr_b16 v[150:151], v86 offset:43584
	ds_read_b64_tr_b16 v[152:153], v86 offset:44672
	ds_read_b64_tr_b16 v[240:241], v86 offset:43616
	ds_read_b64_tr_b16 v[242:243], v86 offset:44704
	s_nop 3
	v_pk_mul_f32 v[66:67], v[58:59], v[66:67]
	v_pk_mul_f32 v[64:65], v[56:57], v[64:65]
	v_pk_fma_f32 v[104:105], v[104:105], v[46:47], v[66:67]
	v_pk_fma_f32 v[102:103], v[102:103], v[44:45], v[64:65]
	v_pk_mul_f32 v[238:239], v[58:59], v[238:239]
	v_pk_mul_f32 v[236:237], v[56:57], v[236:237]
	v_pk_fma_f32 v[114:115], v[114:115], v[46:47], v[238:239]
	v_pk_fma_f32 v[108:109], v[108:109], v[44:45], v[236:237]
	s_waitcnt lgkmcnt(6)
	v_mfma_f32_16x16x32_bf16 v[64:67], v[60:63], v[244:247], 0
	s_waitcnt lgkmcnt(4)
	v_mfma_f32_16x16x32_bf16 v[236:239], v[60:63], v[228:231], 0
	s_waitcnt lgkmcnt(2)
	v_mfma_f32_16x16x32_bf16 v[64:67], v[48:51], v[150:153], v[64:67]
	s_waitcnt lgkmcnt(0)
	v_mfma_f32_16x16x32_bf16 v[236:239], v[48:51], v[240:243], v[236:239]
	ds_read_b64_tr_b16 v[244:245], v86 offset:34944
	ds_read_b64_tr_b16 v[246:247], v86 offset:36032
	ds_read_b64_tr_b16 v[228:229], v86 offset:34976
	ds_read_b64_tr_b16 v[230:231], v86 offset:36064
	ds_read_b64_tr_b16 v[150:151], v86 offset:43648
	ds_read_b64_tr_b16 v[152:153], v86 offset:44736
	ds_read_b64_tr_b16 v[240:241], v86 offset:43680
	ds_read_b64_tr_b16 v[242:243], v86 offset:44768
	s_nop 3
	v_pk_mul_f32 v[66:67], v[58:59], v[66:67]
	v_pk_mul_f32 v[64:65], v[56:57], v[64:65]
	v_pk_fma_f32 v[112:113], v[112:113], v[46:47], v[66:67]
	v_pk_fma_f32 v[106:107], v[106:107], v[44:45], v[64:65]
	v_pk_mul_f32 v[238:239], v[58:59], v[238:239]
	v_pk_mul_f32 v[236:237], v[56:57], v[236:237]
	v_pk_fma_f32 v[118:119], v[118:119], v[46:47], v[238:239]
	v_pk_fma_f32 v[110:111], v[110:111], v[44:45], v[236:237]
	s_waitcnt lgkmcnt(6)
	v_mfma_f32_16x16x32_bf16 v[64:67], v[60:63], v[244:247], 0
	s_waitcnt lgkmcnt(4)
	v_mfma_f32_16x16x32_bf16 v[236:239], v[60:63], v[228:231], 0
	s_waitcnt lgkmcnt(2)
	v_mfma_f32_16x16x32_bf16 v[64:67], v[48:51], v[150:153], v[64:67]
	s_waitcnt lgkmcnt(0)
	v_mfma_f32_16x16x32_bf16 v[236:239], v[48:51], v[240:243], v[236:239]
	ds_read_b64_tr_b16 v[244:245], v86 offset:35008
	ds_read_b64_tr_b16 v[246:247], v86 offset:36096
	ds_read_b64_tr_b16 v[228:229], v86 offset:35040
	ds_read_b64_tr_b16 v[230:231], v86 offset:36128
	ds_read_b64_tr_b16 v[150:151], v86 offset:43712
	ds_read_b64_tr_b16 v[152:153], v86 offset:44800
	ds_read_b64_tr_b16 v[240:241], v86 offset:43744
	ds_read_b64_tr_b16 v[242:243], v86 offset:44832
	s_nop 3
	v_pk_mul_f32 v[66:67], v[58:59], v[66:67]
	v_pk_mul_f32 v[64:65], v[56:57], v[64:65]
	v_pk_fma_f32 v[122:123], v[122:123], v[46:47], v[66:67]
	v_pk_fma_f32 v[116:117], v[116:117], v[44:45], v[64:65]
	v_pk_mul_f32 v[238:239], v[58:59], v[238:239]
	v_pk_mul_f32 v[236:237], v[56:57], v[236:237]
	v_pk_fma_f32 v[126:127], v[126:127], v[46:47], v[238:239]
	v_pk_fma_f32 v[120:121], v[120:121], v[44:45], v[236:237]
	s_waitcnt lgkmcnt(6)
	v_mfma_f32_16x16x32_bf16 v[64:67], v[60:63], v[244:247], 0
	s_waitcnt lgkmcnt(4)
	v_mfma_f32_16x16x32_bf16 v[60:63], v[60:63], v[228:231], 0
	s_waitcnt lgkmcnt(2)
	v_mfma_f32_16x16x32_bf16 v[64:67], v[48:51], v[150:153], v[64:67]
	s_waitcnt lgkmcnt(0)
	s_barrier
	s_waitcnt lgkmcnt(0)
	v_mfma_f32_16x16x32_bf16 v[48:51], v[48:51], v[240:243], v[60:63]
	s_nop 4
	v_pk_mul_f32 v[66:67], v[58:59], v[66:67]
	v_pk_mul_f32 v[64:65], v[56:57], v[64:65]
	v_pk_fma_f32 v[128:129], v[128:129], v[46:47], v[66:67]
	v_pk_fma_f32 v[124:125], v[124:125], v[44:45], v[64:65]
	s_nop 7
	v_pk_mul_f32 v[48:49], v[56:57], v[48:49]
	v_pk_mul_f32 v[50:51], v[58:59], v[50:51]
	v_pk_fma_f32 v[130:131], v[130:131], v[44:45], v[48:49]
	v_mul_f32_e32 v44, v33, v33
	v_mul_f32_e32 v45, v35, v35
	v_fmac_f32_e32 v44, v32, v32
	v_fmac_f32_e32 v45, v34, v34
	v_pk_fma_f32 v[132:133], v[132:133], v[46:47], v[50:51]
	v_add_f32_e32 v44, v44, v45
	v_mul_f32_e32 v45, v37, v37
	v_mul_f32_e32 v46, v39, v39
	v_fmac_f32_e32 v45, v36, v36
	v_fmac_f32_e32 v46, v38, v38
	v_add_f32_e32 v45, v45, v46
	v_add_f32_e32 v44, v44, v45
	v_mul_f32_e32 v45, v53, v53
	v_mul_f32_e32 v46, v55, v55
	v_fmac_f32_e32 v45, v52, v52
	v_fmac_f32_e32 v46, v54, v54
	v_add_f32_e32 v45, v45, v46
	v_add_f32_e32 v44, v44, v45
	v_mul_f32_e32 v45, v41, v41
	v_mul_f32_e32 v46, v43, v43
	v_fmac_f32_e32 v45, v40, v40
	v_fmac_f32_e32 v46, v42, v42
	v_add_f32_e32 v45, v45, v46
	v_and_b32_e32 v46, 64, v210
	v_add_f32_e32 v44, v44, v45
	v_xor_b32_e32 v45, 16, v210
	v_add_u32_e32 v46, 64, v46
	v_cmp_lt_i32_e32 vcc, v45, v46
	s_nop 1
	v_cndmask_b32_e32 v45, v210, v45, vcc
	v_lshlrev_b32_e32 v228, 2, v45
	ds_bpermute_b32 v45, v228, v44
	s_waitcnt lgkmcnt(0)
	v_add_f32_e32 v44, v44, v45
	v_xor_b32_e32 v45, 32, v210
	v_cmp_lt_i32_e32 vcc, v45, v46
	ds_read_b128 v[46:49], v183
	s_waitcnt lgkmcnt(0)
	v_pk_mul_f32 v[50:51], v[104:105], v[48:49]
	v_pk_mul_f32 v[56:57], v[102:103], v[46:47]
	v_cndmask_b32_e32 v45, v210, v45, vcc
	v_cvt_pk_bf16_f32 v56, v56, v57
	v_cvt_pk_bf16_f32 v57, v50, v51
	ds_write_b64 v223, v[56:57]
	v_pk_mul_f32 v[50:51], v[114:115], v[48:49]
	v_pk_mul_f32 v[56:57], v[108:109], v[46:47]
	v_lshlrev_b32_e32 v229, 2, v45
	v_cvt_pk_bf16_f32 v56, v56, v57
	v_cvt_pk_bf16_f32 v57, v50, v51
	ds_write_b64 v223, v[56:57] offset:4352
	v_pk_mul_f32 v[50:51], v[112:113], v[48:49]
	v_pk_mul_f32 v[56:57], v[106:107], v[46:47]
	ds_bpermute_b32 v45, v229, v44
	v_cvt_pk_bf16_f32 v56, v56, v57
	v_cvt_pk_bf16_f32 v57, v50, v51
	ds_write_b64 v223, v[56:57] offset:8704
	v_pk_mul_f32 v[50:51], v[118:119], v[48:49]
	v_pk_mul_f32 v[56:57], v[110:111], v[46:47]
	s_nop 0
	v_cvt_pk_bf16_f32 v56, v56, v57
	v_cvt_pk_bf16_f32 v57, v50, v51
	ds_write_b64 v223, v[56:57] offset:13056
	v_pk_mul_f32 v[50:51], v[122:123], v[48:49]
	v_pk_mul_f32 v[56:57], v[116:117], v[46:47]
	s_nop 0
	v_cvt_pk_bf16_f32 v56, v56, v57
	v_cvt_pk_bf16_f32 v57, v50, v51
	ds_write_b64 v223, v[56:57] offset:17408
	v_pk_mul_f32 v[50:51], v[126:127], v[48:49]
	v_pk_mul_f32 v[56:57], v[120:121], v[46:47]
	s_nop 0
	v_cvt_pk_bf16_f32 v56, v56, v57
	v_cvt_pk_bf16_f32 v57, v50, v51
	ds_write_b64 v223, v[56:57] offset:21760
	v_pk_mul_f32 v[50:51], v[128:129], v[48:49]
	v_pk_mul_f32 v[56:57], v[124:125], v[46:47]
	v_pk_mul_f32 v[48:49], v[132:133], v[48:49]
	v_pk_mul_f32 v[46:47], v[130:131], v[46:47]
	v_cvt_pk_bf16_f32 v56, v56, v57
	v_cvt_pk_bf16_f32 v57, v50, v51
	v_cvt_pk_bf16_f32 v46, v46, v47
	v_cvt_pk_bf16_f32 v47, v48, v49
	ds_write_b64 v223, v[56:57] offset:26112
	ds_write_b64 v223, v[46:47] offset:30464
	s_and_saveexec_b64 s[72:73], s[16:17]
	s_cbranch_execz .LBB0_527
	s_waitcnt lgkmcnt(6)
	v_add_f32_e32 v44, v44, v45
	ds_write_b32 v184, v44

.LBB0_529:
	s_min_u32 s52, s91, 29
	s_lshl_b32 s52, s52, 6
	s_add_i32 s66, s52, 0x80
	s_min_u32 s52, s91, 27
	s_lshl_b32 s52, s52, 6
	s_add_i32 s54, s52, 0x100
	s_add_u32 s52, s62, s54
	s_addc_u32 s53, s63, 0
	v_add_u32_e32 v32, v161, v162
	s_add_u32 s54, s60, s54
	s_waitcnt vmcnt(27)
	ds_write_b128 v32, v[24:27] offset:34816
	v_add_u32_e32 v24, v161, v163
	s_addc_u32 s55, 0, 0
	s_waitcnt vmcnt(26)
	ds_write_b128 v24, v[28:31] offset:34816
	v_lshl_add_u64 v[24:25], v[88:89], 0, s[66:67]
	s_add_u32 s58, s52, s86
	v_lshlrev_b64 v[24:25], 8, v[24:25]
	s_addc_u32 s59, s53, 0
	v_lshl_add_u64 v[24:25], v[90:91], 0, v[24:25]
	s_lshl_b64 s[58:59], s[58:59], 8
	global_load_dwordx2 v[84:85], v[24:25], off
	global_load_dwordx2 v[82:83], v[24:25], off offset:32
	global_load_dwordx2 v[78:79], v[24:25], off offset:64
	global_load_dwordx2 v[76:77], v[24:25], off offset:96
	v_lshl_add_u64 v[24:25], v[70:71], 0, s[58:59]
	s_lshl_b64 s[54:55], s[54:55], 11
	global_load_dword v145, v[24:25], off
	v_lshl_add_u64 v[24:25], v[72:73], 0, s[54:55]
	s_or_b32 s54, s58, 0x100
	s_mov_b32 s55, s59
	v_lshl_add_u64 v[26:27], v[70:71], 0, s[54:55]
	s_or_b32 s54, s58, 0x200
	global_load_dword v144, v[24:25], off
	global_load_dword v146, v[26:27], off
	global_load_dword v143, v[24:25], off offset:2048
	v_lshl_add_u64 v[26:27], v[70:71], 0, s[54:55]
	global_load_dword v138, v[26:27], off
	v_add_co_u32_e32 v26, vcc, s61, v24
	s_or_b32 s54, s58, 0x300
	s_nop 0
	v_addc_co_u32_e32 v27, vcc, 0, v25, vcc
	v_add_co_u32_e32 v28, vcc, s87, v24
	v_lshl_add_u64 v[30:31], v[70:71], 0, s[54:55]
	s_nop 0
	v_addc_co_u32_e32 v29, vcc, 0, v25, vcc
	s_or_b32 s54, s58, 0x400
	global_load_dword v136, v[28:29], off offset:-4096
	global_load_dword v137, v[30:31], off
	global_load_dword v142, v[26:27], off offset:2048
	v_lshl_add_u64 v[26:27], v[70:71], 0, s[54:55]
	s_or_b32 s54, s58, 0x500
	global_load_dword v135, v[26:27], off
	global_load_dword v134, v[28:29], off
	v_lshl_add_u64 v[26:27], v[70:71], 0, s[54:55]
	s_or_b32 s54, s58, 0x600
	v_add_co_u32_e32 v24, vcc, s88, v24
	global_load_dword v139, v[26:27], off
	global_load_dword v141, v[28:29], off offset:2048
	v_lshl_add_u64 v[26:27], v[70:71], 0, s[54:55]
	v_addc_co_u32_e32 v25, vcc, 0, v25, vcc
	s_or_b32 s58, s58, 0x700
	global_load_dword v148, v[26:27], off
	global_load_dword v147, v[24:25], off
	v_lshl_add_u64 v[26:27], v[70:71], 0, s[58:59]
	global_load_dword v140, v[26:27], off
	global_load_dword v155, v[24:25], off offset:2048
	v_mov_b32_e32 v25, s53
	v_or_b32_e32 v24, s52, v93
	v_lshl_add_u64 v[28:29], s[52:53], 0, v[68:69]
	v_lshlrev_b64 v[24:25], 8, v[24:25]
	v_lshlrev_b64 v[28:29], 8, v[28:29]
	v_lshl_add_u64 v[24:25], v[74:75], 0, v[24:25]
	v_lshl_add_u64 v[28:29], v[74:75], 0, v[28:29]
	global_load_dwordx4 v[24:27], v[24:25], off
	s_nop 0
	global_load_dwordx4 v[28:31], v[28:29], off
	ds_read_b128 v[52:55], v218 offset:52224
	ds_read_b128 v[48:51], v218 offset:52288
	ds_read_b128 v[44:47], v218 offset:52352
	ds_read_b128 v[36:39], v218 offset:52416
	ds_read_b128 v[32:35], v211
	ds_read_b128 v[40:43], v211 offset:64
	s_waitcnt lgkmcnt(1)
	v_mfma_f32_16x16x32_bf16 v[32:35], v[32:35], v[52:55], 0
	s_waitcnt lgkmcnt(0)
	v_mfma_f32_16x16x32_bf16 v[32:35], v[40:43], v[48:51], v[32:35]
	ds_read_b128 v[40:43], v211 offset:128
	s_waitcnt lgkmcnt(0)
	v_mfma_f32_16x16x32_bf16 v[32:35], v[40:43], v[44:47], v[32:35]
	ds_read_b128 v[40:43], v211 offset:192
	s_waitcnt lgkmcnt(0)
	v_mfma_f32_16x16x32_bf16 v[32:35], v[40:43], v[36:39], v[32:35]
	ds_read_b128 v[40:43], v211 offset:4416
	s_nop 6
	v_cndmask_b32_e64 v56, 0, v32, s[18:19]
	v_cndmask_b32_e64 v57, 0, v33, s[20:21]
	v_cndmask_b32_e64 v58, 0, v34, s[22:23]
	v_cndmask_b32_e64 v59, 0, v35, s[24:25]
	ds_read_b128 v[32:35], v211 offset:4352
	s_waitcnt lgkmcnt(0)
	v_mfma_f32_16x16x32_bf16 v[32:35], v[32:35], v[52:55], 0
	v_cvt_pk_bf16_f32 v64, v56, v57
	v_cvt_pk_bf16_f32 v65, v58, v59
	v_mfma_f32_16x16x32_bf16 v[32:35], v[40:43], v[48:51], v[32:35]
	ds_read_b128 v[40:43], v211 offset:4480
	s_waitcnt lgkmcnt(0)
	v_mfma_f32_16x16x32_bf16 v[32:35], v[40:43], v[44:47], v[32:35]
	ds_read_b128 v[40:43], v211 offset:4544
	s_waitcnt lgkmcnt(0)
	v_mfma_f32_16x16x32_bf16 v[32:35], v[40:43], v[36:39], v[32:35]
	ds_read_b128 v[40:43], v211 offset:8768
	s_nop 6
	v_cndmask_b32_e64 v60, 0, v32, s[26:27]
	v_cndmask_b32_e64 v61, 0, v33, s[28:29]
	v_cndmask_b32_e64 v62, 0, v34, s[30:31]
	v_cndmask_b32_e64 v63, 0, v35, s[34:35]
	ds_read_b128 v[32:35], v211 offset:8704
	s_waitcnt lgkmcnt(0)
	v_mfma_f32_16x16x32_bf16 v[32:35], v[32:35], v[52:55], 0
	v_cvt_pk_bf16_f32 v67, v62, v63
	v_cvt_pk_bf16_f32 v66, v60, v61
	v_mfma_f32_16x16x32_bf16 v[32:35], v[40:43], v[48:51], v[32:35]
	ds_read_b128 v[40:43], v211 offset:8832
	s_waitcnt lgkmcnt(0)
	v_mfma_f32_16x16x32_bf16 v[32:35], v[40:43], v[44:47], v[32:35]
	ds_read_b128 v[40:43], v211 offset:8896
	s_waitcnt lgkmcnt(0)
	v_mfma_f32_16x16x32_bf16 v[32:35], v[40:43], v[36:39], v[32:35]
	ds_read_b128 v[40:43], v211 offset:13120
	s_nop 6
	v_cndmask_b32_e64 v86, 0, v32, s[36:37]
	v_cndmask_b32_e64 v149, 0, v33, s[38:39]
	v_cndmask_b32_e64 v150, 0, v34, s[40:41]
	v_cndmask_b32_e64 v151, 0, v35, s[42:43]
	ds_read_b128 v[32:35], v211 offset:13056
	s_waitcnt lgkmcnt(0)
	v_mfma_f32_16x16x32_bf16 v[32:35], v[32:35], v[52:55], 0
	v_cvt_pk_bf16_f32 v60, v86, v149
	v_cvt_pk_bf16_f32 v61, v150, v151
	v_add_u32_e32 v86, v192, v203
	v_mfma_f32_16x16x32_bf16 v[32:35], v[40:43], v[48:51], v[32:35]
	ds_read_b128 v[40:43], v211 offset:13184
	s_waitcnt lgkmcnt(0)
	v_mfma_f32_16x16x32_bf16 v[32:35], v[40:43], v[44:47], v[32:35]
	ds_read_b128 v[40:43], v211 offset:13248
	s_waitcnt lgkmcnt(0)
	v_mfma_f32_16x16x32_bf16 v[32:35], v[40:43], v[36:39], v[32:35]
	s_nop 7
	v_cndmask_b32_e64 v32, 0, v32, s[44:45]
	v_cndmask_b32_e64 v33, 0, v33, s[46:47]
	v_cndmask_b32_e64 v34, 0, v34, s[48:49]
	v_cndmask_b32_e64 v35, 0, v35, s[50:51]
	v_cvt_pk_bf16_f32 v62, v32, v33
	v_cvt_pk_bf16_f32 v63, v34, v35
	ds_read_b64_tr_b16 v[32:33], v212
	ds_read_b64_tr_b16 v[34:35], v212 offset:4352
	ds_read_b64_tr_b16 v[40:41], v212 offset:8704
	ds_read_b64_tr_b16 v[42:43], v212 offset:13056
	s_waitcnt lgkmcnt(2)
	v_mfma_f32_16x16x32_bf16 v[32:35], v[32:35], v[64:67], 0
	s_waitcnt lgkmcnt(0)
	v_mfma_f32_16x16x32_bf16 v[32:35], v[40:43], v[60:63], v[32:35]
	ds_read_b128 v[40:43], v219
	s_waitcnt lgkmcnt(0)
	v_mfma_f32_16x16x32_bf16 v[32:35], v[40:43], v[52:55], v[32:35]
	ds_read_b128 v[40:43], v219 offset:64
	s_waitcnt lgkmcnt(0)
	v_mfma_f32_16x16x32_bf16 v[32:35], v[40:43], v[48:51], v[32:35]
	ds_read_b128 v[40:43], v219 offset:128
	s_waitcnt lgkmcnt(0)
	v_mfma_f32_16x16x32_bf16 v[32:35], v[40:43], v[44:47], v[32:35]
	ds_read_b128 v[40:43], v219 offset:192
	s_waitcnt lgkmcnt(0)
	v_mfma_f32_16x16x32_bf16 v[32:35], v[40:43], v[36:39], v[32:35]
	ds_read_b64_tr_b16 v[40:41], v214
	ds_read_b64_tr_b16 v[42:43], v214 offset:4352
	ds_read_b64_tr_b16 v[56:57], v214 offset:8704
	ds_read_b64_tr_b16 v[58:59], v214 offset:13056
	s_waitcnt lgkmcnt(2)
	v_mfma_f32_16x16x32_bf16 v[40:43], v[40:43], v[64:67], 0
	s_waitcnt lgkmcnt(0)
	v_mfma_f32_16x16x32_bf16 v[40:43], v[56:59], v[60:63], v[40:43]
	ds_read_b128 v[56:59], v220
	s_waitcnt lgkmcnt(0)
	v_mfma_f32_16x16x32_bf16 v[40:43], v[56:59], v[52:55], v[40:43]
	ds_read_b128 v[56:59], v220 offset:64
	s_waitcnt lgkmcnt(0)
	v_mfma_f32_16x16x32_bf16 v[40:43], v[56:59], v[48:51], v[40:43]
	ds_read_b128 v[56:59], v220 offset:128
	s_waitcnt lgkmcnt(0)
	v_mfma_f32_16x16x32_bf16 v[40:43], v[56:59], v[44:47], v[40:43]
	ds_read_b128 v[56:59], v220 offset:192
	s_waitcnt lgkmcnt(0)
	v_mfma_f32_16x16x32_bf16 v[40:43], v[56:59], v[36:39], v[40:43]
	ds_read_b64_tr_b16 v[56:57], v215
	ds_read_b64_tr_b16 v[58:59], v215 offset:4352
	ds_read_b64_tr_b16 v[150:151], v215 offset:8704
	ds_read_b64_tr_b16 v[152:153], v215 offset:13056
	s_waitcnt lgkmcnt(2)
	v_mfma_f32_16x16x32_bf16 v[56:59], v[56:59], v[64:67], 0
	s_waitcnt lgkmcnt(0)
	v_mfma_f32_16x16x32_bf16 v[56:59], v[150:153], v[60:63], v[56:59]
	ds_read_b128 v[150:153], v221
	s_waitcnt lgkmcnt(0)
	v_mfma_f32_16x16x32_bf16 v[56:59], v[150:153], v[52:55], v[56:59]
	ds_read_b128 v[150:153], v221 offset:64
	s_waitcnt lgkmcnt(0)
	v_mfma_f32_16x16x32_bf16 v[56:59], v[150:153], v[48:51], v[56:59]
	ds_read_b128 v[150:153], v221 offset:128
	s_waitcnt lgkmcnt(0)
	v_mfma_f32_16x16x32_bf16 v[56:59], v[150:153], v[44:47], v[56:59]
	ds_read_b128 v[150:153], v221 offset:192
	s_waitcnt lgkmcnt(0)
	v_mfma_f32_16x16x32_bf16 v[56:59], v[150:153], v[36:39], v[56:59]
	ds_read_b64_tr_b16 v[150:151], v216
	ds_read_b64_tr_b16 v[152:153], v216 offset:4352
	s_waitcnt lgkmcnt(0)
	v_mfma_f32_16x16x32_bf16 v[64:67], v[150:153], v[64:67], 0
	ds_read_b64_tr_b16 v[150:151], v216 offset:8704
	ds_read_b64_tr_b16 v[152:153], v216 offset:13056
	s_waitcnt lgkmcnt(0)
	v_mfma_f32_16x16x32_bf16 v[60:63], v[150:153], v[60:63], v[64:67]
	s_nop 3
	ds_read_b128 v[64:67], v222
	s_waitcnt lgkmcnt(0)
	v_mfma_f32_16x16x32_bf16 v[52:55], v[64:67], v[52:55], v[60:63]
	s_nop 2
	ds_read_b128 v[60:63], v222 offset:64
	s_waitcnt lgkmcnt(0)
	v_mfma_f32_16x16x32_bf16 v[48:51], v[60:63], v[48:51], v[52:55]
	s_nop 2
	ds_read_b128 v[52:55], v222 offset:128
	s_waitcnt lgkmcnt(0)
	v_mfma_f32_16x16x32_bf16 v[44:47], v[52:55], v[44:47], v[48:51]
	s_nop 2
	ds_read_b128 v[48:51], v222 offset:192
	s_waitcnt lgkmcnt(0)
	v_mfma_f32_16x16x32_bf16 v[36:39], v[48:51], v[36:39], v[44:47]
	ds_read_b64_tr_b16 v[60:61], v217
	ds_read_b64_tr_b16 v[62:63], v217 offset:1088
	ds_read_b64_tr_b16 v[52:53], v217 offset:8704
	ds_read_b64_tr_b16 v[54:55], v217 offset:9792
	ds_read_b128 v[44:47], v193
	ds_read_b128 v[48:51], v195
	ds_read_b64_tr_b16 v[244:245], v86
	ds_read_b64_tr_b16 v[246:247], v86 offset:1088
	ds_read_b64_tr_b16 v[230:231], v86 offset:32
	ds_read_b64_tr_b16 v[232:233], v86 offset:1120
	ds_read_b64_tr_b16 v[150:151], v86 offset:8704
	ds_read_b64_tr_b16 v[152:153], v86 offset:9792
	ds_read_b64_tr_b16 v[240:241], v86 offset:8736
	ds_read_b64_tr_b16 v[242:243], v86 offset:9824
	s_waitcnt lgkmcnt(6)
	v_mfma_f32_16x16x32_bf16 v[64:67], v[60:63], v[244:247], 0
	s_waitcnt lgkmcnt(4)
	v_mfma_f32_16x16x32_bf16 v[236:239], v[60:63], v[230:233], 0
	s_waitcnt lgkmcnt(2)
	v_mfma_f32_16x16x32_bf16 v[64:67], v[52:55], v[150:153], v[64:67]
	s_waitcnt lgkmcnt(0)
	v_mfma_f32_16x16x32_bf16 v[236:239], v[52:55], v[240:243], v[236:239]
	ds_read_b64_tr_b16 v[244:245], v86 offset:64
	ds_read_b64_tr_b16 v[246:247], v86 offset:1152
	ds_read_b64_tr_b16 v[230:231], v86 offset:96
	ds_read_b64_tr_b16 v[232:233], v86 offset:1184
	ds_read_b64_tr_b16 v[150:151], v86 offset:8768
	ds_read_b64_tr_b16 v[152:153], v86 offset:9856
	ds_read_b64_tr_b16 v[240:241], v86 offset:8800
	ds_read_b64_tr_b16 v[242:243], v86 offset:9888
	s_nop 3
	v_pk_mul_f32 v[66:67], v[50:51], v[66:67]
	v_pk_mul_f32 v[64:65], v[48:49], v[64:65]
	v_pk_fma_f32 v[104:105], v[104:105], v[46:47], v[66:67]
	v_pk_fma_f32 v[102:103], v[102:103], v[44:45], v[64:65]
	v_pk_mul_f32 v[238:239], v[50:51], v[238:239]
	v_pk_mul_f32 v[236:237], v[48:49], v[236:237]
	v_pk_fma_f32 v[114:115], v[114:115], v[46:47], v[238:239]
	v_pk_fma_f32 v[108:109], v[108:109], v[44:45], v[236:237]
	s_waitcnt lgkmcnt(6)
	v_mfma_f32_16x16x32_bf16 v[64:67], v[60:63], v[244:247], 0
	s_waitcnt lgkmcnt(4)
	v_mfma_f32_16x16x32_bf16 v[236:239], v[60:63], v[230:233], 0
	s_waitcnt lgkmcnt(2)
	v_mfma_f32_16x16x32_bf16 v[64:67], v[52:55], v[150:153], v[64:67]
	s_waitcnt lgkmcnt(0)
	v_mfma_f32_16x16x32_bf16 v[236:239], v[52:55], v[240:243], v[236:239]
	ds_read_b64_tr_b16 v[244:245], v86 offset:128
	ds_read_b64_tr_b16 v[246:247], v86 offset:1216
	ds_read_b64_tr_b16 v[230:231], v86 offset:160
	ds_read_b64_tr_b16 v[232:233], v86 offset:1248
	ds_read_b64_tr_b16 v[150:151], v86 offset:8832
	ds_read_b64_tr_b16 v[152:153], v86 offset:9920
	ds_read_b64_tr_b16 v[240:241], v86 offset:8864
	ds_read_b64_tr_b16 v[242:243], v86 offset:9952
	s_nop 3
	v_pk_mul_f32 v[66:67], v[50:51], v[66:67]
	v_pk_mul_f32 v[64:65], v[48:49], v[64:65]
	v_pk_fma_f32 v[112:113], v[112:113], v[46:47], v[66:67]
	v_pk_fma_f32 v[106:107], v[106:107], v[44:45], v[64:65]
	v_pk_mul_f32 v[238:239], v[50:51], v[238:239]
	v_pk_mul_f32 v[236:237], v[48:49], v[236:237]
	v_pk_fma_f32 v[118:119], v[118:119], v[46:47], v[238:239]
	v_pk_fma_f32 v[110:111], v[110:111], v[44:45], v[236:237]
	s_waitcnt lgkmcnt(6)
	v_mfma_f32_16x16x32_bf16 v[64:67], v[60:63], v[244:247], 0
	s_waitcnt lgkmcnt(4)
	v_mfma_f32_16x16x32_bf16 v[236:239], v[60:63], v[230:233], 0
	s_waitcnt lgkmcnt(2)
	v_mfma_f32_16x16x32_bf16 v[64:67], v[52:55], v[150:153], v[64:67]
	s_waitcnt lgkmcnt(0)
	v_mfma_f32_16x16x32_bf16 v[236:239], v[52:55], v[240:243], v[236:239]
	ds_read_b64_tr_b16 v[244:245], v86 offset:192
	ds_read_b64_tr_b16 v[246:247], v86 offset:1280
	ds_read_b64_tr_b16 v[230:231], v86 offset:224
	ds_read_b64_tr_b16 v[232:233], v86 offset:1312
	ds_read_b64_tr_b16 v[150:151], v86 offset:8896
	ds_read_b64_tr_b16 v[152:153], v86 offset:9984
	ds_read_b64_tr_b16 v[240:241], v86 offset:8928
	ds_read_b64_tr_b16 v[242:243], v86 offset:10016
	s_nop 3
	v_pk_mul_f32 v[66:67], v[50:51], v[66:67]
	v_pk_mul_f32 v[64:65], v[48:49], v[64:65]
	v_pk_fma_f32 v[122:123], v[122:123], v[46:47], v[66:67]
	v_pk_fma_f32 v[116:117], v[116:117], v[44:45], v[64:65]
	v_pk_mul_f32 v[238:239], v[50:51], v[238:239]
	v_pk_mul_f32 v[236:237], v[48:49], v[236:237]
	v_pk_fma_f32 v[126:127], v[126:127], v[46:47], v[238:239]
	v_pk_fma_f32 v[120:121], v[120:121], v[44:45], v[236:237]
	s_waitcnt lgkmcnt(6)
	v_mfma_f32_16x16x32_bf16 v[64:67], v[60:63], v[244:247], 0
	s_waitcnt lgkmcnt(4)
	v_mfma_f32_16x16x32_bf16 v[60:63], v[60:63], v[230:233], 0
	s_waitcnt lgkmcnt(2)
	v_mfma_f32_16x16x32_bf16 v[64:67], v[52:55], v[150:153], v[64:67]
	s_waitcnt lgkmcnt(0)
	s_barrier
	s_waitcnt lgkmcnt(0)
	v_mfma_f32_16x16x32_bf16 v[52:55], v[52:55], v[240:243], v[60:63]
	s_nop 4
	v_pk_mul_f32 v[66:67], v[50:51], v[66:67]
	v_pk_mul_f32 v[64:65], v[48:49], v[64:65]
	v_pk_fma_f32 v[128:129], v[128:129], v[46:47], v[66:67]
	v_pk_fma_f32 v[124:125], v[124:125], v[44:45], v[64:65]
	s_nop 7
	v_pk_mul_f32 v[48:49], v[48:49], v[52:53]
	v_pk_mul_f32 v[50:51], v[50:51], v[54:55]
	v_pk_fma_f32 v[130:131], v[130:131], v[44:45], v[48:49]
	v_mul_f32_e32 v44, v33, v33
	v_mul_f32_e32 v45, v35, v35
	v_fmac_f32_e32 v44, v32, v32
	v_fmac_f32_e32 v45, v34, v34
	v_pk_fma_f32 v[132:133], v[132:133], v[46:47], v[50:51]
	v_add_f32_e32 v44, v44, v45
	v_mul_f32_e32 v45, v41, v41
	v_mul_f32_e32 v46, v43, v43
	v_fmac_f32_e32 v45, v40, v40
	v_fmac_f32_e32 v46, v42, v42
	v_add_f32_e32 v45, v45, v46
	v_add_f32_e32 v44, v44, v45
	v_mul_f32_e32 v45, v57, v57
	v_mul_f32_e32 v46, v59, v59
	v_fmac_f32_e32 v45, v56, v56
	v_fmac_f32_e32 v46, v58, v58
	v_add_f32_e32 v45, v45, v46
	v_add_f32_e32 v44, v44, v45
	v_mul_f32_e32 v45, v37, v37
	v_mul_f32_e32 v46, v39, v39
	v_fmac_f32_e32 v45, v36, v36
	v_fmac_f32_e32 v46, v38, v38
	v_add_f32_e32 v45, v45, v46
	ds_read_b128 v[46:49], v197
	v_add_f32_e32 v44, v44, v45
	ds_bpermute_b32 v45, v228, v44
	s_waitcnt lgkmcnt(1)
	v_pk_mul_f32 v[50:51], v[104:105], v[48:49]
	v_pk_mul_f32 v[52:53], v[102:103], v[46:47]
	s_waitcnt lgkmcnt(0)
	v_add_f32_e32 v44, v44, v45
	v_cvt_pk_bf16_f32 v52, v52, v53
	v_cvt_pk_bf16_f32 v53, v50, v51
	ds_write_b64 v223, v[52:53]
	v_pk_mul_f32 v[50:51], v[114:115], v[48:49]
	v_pk_mul_f32 v[52:53], v[108:109], v[46:47]
	ds_bpermute_b32 v45, v229, v44
	v_cvt_pk_bf16_f32 v52, v52, v53
	v_cvt_pk_bf16_f32 v53, v50, v51
	ds_write_b64 v223, v[52:53] offset:4352
	v_pk_mul_f32 v[50:51], v[112:113], v[48:49]
	v_pk_mul_f32 v[52:53], v[106:107], v[46:47]
	s_nop 0
	v_cvt_pk_bf16_f32 v52, v52, v53
	v_cvt_pk_bf16_f32 v53, v50, v51
	ds_write_b64 v223, v[52:53] offset:8704
	v_pk_mul_f32 v[50:51], v[118:119], v[48:49]
	v_pk_mul_f32 v[52:53], v[110:111], v[46:47]
	s_nop 0
	v_cvt_pk_bf16_f32 v52, v52, v53
	v_cvt_pk_bf16_f32 v53, v50, v51
	ds_write_b64 v223, v[52:53] offset:13056
	v_pk_mul_f32 v[50:51], v[122:123], v[48:49]
	v_pk_mul_f32 v[52:53], v[116:117], v[46:47]
	s_nop 0
	v_cvt_pk_bf16_f32 v52, v52, v53
	v_cvt_pk_bf16_f32 v53, v50, v51
	ds_write_b64 v223, v[52:53] offset:17408
	v_pk_mul_f32 v[50:51], v[126:127], v[48:49]
	v_pk_mul_f32 v[52:53], v[120:121], v[46:47]
	s_nop 0
	v_cvt_pk_bf16_f32 v52, v52, v53
	v_cvt_pk_bf16_f32 v53, v50, v51
	ds_write_b64 v223, v[52:53] offset:21760
	v_pk_mul_f32 v[50:51], v[128:129], v[48:49]
	v_pk_mul_f32 v[52:53], v[124:125], v[46:47]
	v_pk_mul_f32 v[48:49], v[132:133], v[48:49]
	v_pk_mul_f32 v[46:47], v[130:131], v[46:47]
	v_cvt_pk_bf16_f32 v52, v52, v53
	v_cvt_pk_bf16_f32 v53, v50, v51
	v_cvt_pk_bf16_f32 v46, v46, v47
	v_cvt_pk_bf16_f32 v47, v48, v49
	ds_write_b64 v223, v[52:53] offset:26112
	ds_write_b64 v223, v[46:47] offset:30464
	s_and_saveexec_b64 s[52:53], s[16:17]
	s_cbranch_execz .LBB0_500
	s_waitcnt lgkmcnt(7)
	v_add_f32_e32 v44, v44, v45
	ds_write_b32 v184, v44
	s_branch .LBB0_500
